# P2 pool-unit rebalancing guarded by gridDim.x==256 (falls back to the original unit order otherwise)
# speedup vs baseline: 1.0040x; 1.0040x over previous
; __device__ __forceinline__ void mixer_phase(const Params& p, LAS unsigned char* lds) {
;     ...
;     for (int u = bx; u < 1024; u += G) {
;         const int tt = u >> 2, g = u & 3, b = tt >> 5, t0 = (tt & 31) * 64, grow0 = b * T + t0, w = 2 << g;
;         POOL_LOADW(g);
;         u32x4 cp[3];
; #pragma unroll
;         for (int i = 0; i < 3; ++i) cp[i] = pq[i];
;         if (u + G < 1024) POOL_PREFETCH(u + G);
.LBB0_291:
	s_add_i32 s76, s77, s3
	s_cmpk_gt_i32 s76, 0x3ff
	s_cselect_b64 s[74:75], -1, 0
	s_cmp_lg_u32 s3, 0x100
	s_cbranch_scc1 .Lmy_p2std
	s_cmp_lt_u32 s2, 48
	s_movk_i32 s98, 0x3ff
	s_cselect_b32 s98, 0x1ff, s98
	s_cmp_gt_i32 s76, s98
	s_cselect_b64 s[74:75], -1, 0
	s_sub_u32 s100, s2, 48
	s_cmp_lt_u32 s100, 0x60
	s_cbranch_scc0 .Lmy_p2std
	s_cmp_eq_u32 s99, 0
	s_cbranch_scc0 .Lmy_p2fin
	s_cmp_gt_i32 s76, 0x3ff
	s_cbranch_scc0 .Lmy_p2std
	s_mov_b32 s99, 1
	s_add_i32 s76, s2, 0x1d0
	s_cmp_lt_u32 s100, 48
	s_cbranch_scc1 .Lmy_p2set
	s_add_i32 s76, s2, 0x2a0
